# phase-1 W1 convert items: the four tile loads and gain loads issued together before one wait (was a load-wait ladder); NSA top-k of the second virtual block moved to its own SIMD
# speedup vs baseline: 1.0859x; 1.0012x over previous
; DEVI void nsa_item(const Params& p, int l, int item, char* lds_raw, volatile int* nsa_cnt) {
;     ...
;   if (tid < 64) {
;     const int cur = qt;
;     unsigned forced = 1u | (1u << cur) | (cur > 0 ? (1u << (cur - 1)) : 0u);
;     unsigned sel = forced;
;     int cnt = __popc(forced);
;     for (int J = 0; J < 32; ++J) {
;       float v = Gs[tid * 33 + J];
;       if (J > 0) v += Ls_[tid * 33 + J - 1];
;       Pb[tid * 33 + J] = v;
;     }
.LBB0_489:
	s_barrier
	v_lshrrev_b32_e32 v247, 6, v83
	v_lshrrev_b32_e32 v248, 8, v220
	v_cmp_eq_u32_e32 vcc, v247, v248
	v_and_b32_e32 v247, 63, v83
	s_mov_b64 s[4:5], exec
	v_readlane_b32 s88, v242, 47
	v_readlane_b32 s94, v242, 53
	v_readlane_b32 s95, v242, 54
	s_and_b64 s[0:1], s[4:5], vcc
	v_readlane_b32 s89, v242, 48
	v_readlane_b32 s90, v242, 49
	v_readlane_b32 s91, v242, 50
	v_readlane_b32 s92, v242, 51
	v_readlane_b32 s93, v242, 52
	s_mov_b32 s86, s30
	s_mov_b32 s87, s24
	s_mov_b64 s[96:97], s[6:7]
	s_mov_b64 s[6:7], s[18:19]
	s_mov_b32 s18, s29
	s_mov_b32 s19, s33
	s_mov_b32 s33, s22
	s_mov_b32 s22, s13
	v_readlane_b32 s24, v242, 42
	v_readlane_b32 s13, v242, 41
	s_movk_i32 s94, 0x100
	s_movk_i32 s95, 0x880
	s_movk_i32 s83, 0x440
	s_movk_i32 s72, 0x1800
	s_mov_b64 s[2:3], s[16:17]
	s_mov_b32 s16, 0x5040100
	s_mov_b32 s17, 0xa728000
	s_mov_b64 exec, s[0:1]
	s_cbranch_execz .LBB0_498
	s_sub_i32 s1, 30, s28
	s_lshr_b32 s0, 0x80000000, s28
	s_lshl_b32 s1, 1, s1
	s_cmp_lt_i32 s28, 31
	s_cselect_b32 s1, s1, 0
	s_or_b32 s0, s0, s1
	s_movk_i32 s1, 0x84
	v_mul_lo_u32 v53, v247, s1
	v_add_u32_e32 v52, s26, v53
	v_add_u32_e32 v50, 0x9000, v52
	v_add_u32_e32 v54, 0x9004, v52
	v_add_u32_e32 v56, 0xb100, v52
	ds_read2_b32 v[50:51], v50 offset1:31
	ds_read2_b32 v[54:55], v54 offset1:1
	ds_read2_b32 v[56:57], v56 offset1:1
	v_add_u32_e32 v58, 0xd204, v52
	s_or_b32 s0, s0, 1
	s_bcnt1_i32_b32 s30, s0
	s_sub_i32 s38, 32, s28
	s_waitcnt lgkmcnt(0)
	v_pk_add_f32 v[54:55], v[54:55], v[56:57]
	ds_write2_b32 v58, v54, v55 offset1:1
	v_add_u32_e32 v54, 0x900c, v52
	v_add_u32_e32 v56, 0xb108, v52
	ds_read2_b32 v[54:55], v54 offset1:1
	ds_read2_b32 v[56:57], v56 offset1:1
	v_add_u32_e32 v58, 0xd20c, v52
	s_mov_b64 s[36:37], 0
	s_waitcnt lgkmcnt(0)
	v_pk_add_f32 v[54:55], v[54:55], v[56:57]
	ds_write2_b32 v58, v54, v55 offset1:1
	v_add_u32_e32 v54, 0x9014, v52
	v_add_u32_e32 v56, 0xb110, v52
	ds_read2_b32 v[54:55], v54 offset1:1
	ds_read2_b32 v[56:57], v56 offset1:1
	v_add_u32_e32 v58, 0xd214, v52
	s_waitcnt lgkmcnt(0)
	v_pk_add_f32 v[54:55], v[54:55], v[56:57]
	ds_write2_b32 v58, v54, v55 offset1:1
	v_add_u32_e32 v54, 0x901c, v52
	v_add_u32_e32 v56, 0xb118, v52
	ds_read2_b32 v[54:55], v54 offset1:1
	ds_read2_b32 v[56:57], v56 offset1:1
	v_add_u32_e32 v58, 0xd21c, v52
	s_waitcnt lgkmcnt(0)
	v_pk_add_f32 v[54:55], v[54:55], v[56:57]
	ds_write2_b32 v58, v54, v55 offset1:1
	v_add_u32_e32 v54, 0x9024, v52
	v_add_u32_e32 v56, 0xb120, v52
	ds_read2_b32 v[54:55], v54 offset1:1
	ds_read2_b32 v[56:57], v56 offset1:1
	v_add_u32_e32 v58, 0xd224, v52
	s_waitcnt lgkmcnt(0)
	v_pk_add_f32 v[54:55], v[54:55], v[56:57]
	ds_write2_b32 v58, v54, v55 offset1:1
	v_add_u32_e32 v54, 0x902c, v52
	v_add_u32_e32 v56, 0xb128, v52
	ds_read2_b32 v[54:55], v54 offset1:1
	ds_read2_b32 v[56:57], v56 offset1:1
	v_add_u32_e32 v58, 0xd22c, v52
	s_waitcnt lgkmcnt(0)
	v_pk_add_f32 v[54:55], v[54:55], v[56:57]
	ds_write2_b32 v58, v54, v55 offset1:1
	v_add_u32_e32 v54, 0x9034, v52
	v_add_u32_e32 v56, 0xb130, v52
	ds_read2_b32 v[54:55], v54 offset1:1
	ds_read2_b32 v[56:57], v56 offset1:1
	v_add_u32_e32 v58, 0xd234, v52
	s_waitcnt lgkmcnt(0)
	v_pk_add_f32 v[54:55], v[54:55], v[56:57]
	ds_write2_b32 v58, v54, v55 offset1:1
	v_add_u32_e32 v54, 0x903c, v52
	v_add_u32_e32 v56, 0xb138, v52
	ds_read2_b32 v[54:55], v54 offset1:1
	ds_read2_b32 v[56:57], v56 offset1:1
	v_add_u32_e32 v58, 0xd23c, v52
	s_waitcnt lgkmcnt(0)
	v_pk_add_f32 v[54:55], v[54:55], v[56:57]
	ds_write2_b32 v58, v54, v55 offset1:1
	v_add_u32_e32 v54, 0x9044, v52
	v_add_u32_e32 v56, 0xb140, v52
	ds_read2_b32 v[54:55], v54 offset1:1
	ds_read2_b32 v[56:57], v56 offset1:1
	v_add_u32_e32 v58, 0xd244, v52
	s_waitcnt lgkmcnt(0)
	v_pk_add_f32 v[54:55], v[54:55], v[56:57]
	ds_write2_b32 v58, v54, v55 offset1:1
	v_add_u32_e32 v54, 0x904c, v52
	v_add_u32_e32 v56, 0xb148, v52
	ds_read2_b32 v[54:55], v54 offset1:1
	ds_read2_b32 v[56:57], v56 offset1:1
	v_add_u32_e32 v58, 0xd24c, v52
	s_waitcnt lgkmcnt(0)
	v_pk_add_f32 v[54:55], v[54:55], v[56:57]
	ds_write2_b32 v58, v54, v55 offset1:1
	v_add_u32_e32 v54, 0x9054, v52
	v_add_u32_e32 v56, 0xb150, v52
	ds_read2_b32 v[54:55], v54 offset1:1
	ds_read2_b32 v[56:57], v56 offset1:1
	v_add_u32_e32 v58, 0xd254, v52
	s_waitcnt lgkmcnt(0)
	v_pk_add_f32 v[54:55], v[54:55], v[56:57]
	ds_write2_b32 v58, v54, v55 offset1:1
	v_add_u32_e32 v54, 0x905c, v52
	v_add_u32_e32 v56, 0xb158, v52
	ds_read2_b32 v[54:55], v54 offset1:1
	ds_read2_b32 v[56:57], v56 offset1:1
	v_add_u32_e32 v58, 0xd25c, v52
	s_waitcnt lgkmcnt(0)
	v_pk_add_f32 v[54:55], v[54:55], v[56:57]
	ds_write2_b32 v58, v54, v55 offset1:1
	v_add_u32_e32 v54, 0x9064, v52
	v_add_u32_e32 v56, 0xb160, v52
	ds_read2_b32 v[54:55], v54 offset1:1
	ds_read2_b32 v[56:57], v56 offset1:1
	v_add_u32_e32 v58, 0xd264, v52
	s_waitcnt lgkmcnt(0)
	v_pk_add_f32 v[54:55], v[54:55], v[56:57]
	ds_write2_b32 v58, v54, v55 offset1:1
	v_add_u32_e32 v54, 0x906c, v52
	v_add_u32_e32 v56, 0xb168, v52
	ds_read2_b32 v[54:55], v54 offset1:1
	ds_read2_b32 v[56:57], v56 offset1:1
	v_add_u32_e32 v58, 0xd26c, v52
	s_waitcnt lgkmcnt(0)
	v_pk_add_f32 v[54:55], v[54:55], v[56:57]
	ds_write2_b32 v58, v54, v55 offset1:1
	v_add_u32_e32 v54, 0x9074, v52
	v_add_u32_e32 v56, 0xb170, v52
	ds_read2_b32 v[54:55], v54 offset1:1
	ds_read2_b32 v[56:57], v56 offset1:1
	v_add_u32_e32 v58, 0xd274, v52
	s_waitcnt lgkmcnt(0)
	v_pk_add_f32 v[54:55], v[54:55], v[56:57]
	ds_write2_b32 v58, v54, v55 offset1:1
	ds_read_b32 v54, v52 offset:45432
	s_waitcnt lgkmcnt(0)
; DEVI void nsa_item(const Params& p, int l, int item, char* lds_raw, volatile int* nsa_cnt) {
;     ...
;     unsigned forced = 1u | (1u << cur) | (cur > 0 ? (1u << (cur - 1)) : 0u);
;     unsigned sel = forced;
;     int cnt = __popc(forced);
;     for (int J = 0; J < 32; ++J) {
;       float v = Gs[tid * 33 + J];
;       if (J > 0) v += Ls_[tid * 33 + J - 1];
;       Pb[tid * 33 + J] = v;
;     }
;     while (cnt < 8) {
;       int best = -1;
;       float bv = -1.f;
;       for (int J = 0; J <= cur; ++J) {
;         float v = Pb[tid * 33 + J];
;         if (!((sel >> J) & 1u) && v > bv) { bv = v; best = J; }
;       }
;       if (best < 0) break;
;       sel |= 1u << best;
;       ++cnt;
;     }
	v_add_f32_e32 v51, v51, v54
	v_add_u32_e32 v54, 0xd000, v52
	ds_write2_b32 v54, v50, v51 offset0:128 offset1:159
	v_add_u32_e32 v50, s21, v53
	v_mov_b32_e32 v51, s0
	ds_read2_b32 v[54:55], v50 offset0:1 offset1:2
	ds_read2_b32 v[56:57], v50 offset0:3 offset1:4
	ds_read2_b32 v[58:59], v50 offset0:5 offset1:6
	ds_read2_b32 v[60:61], v50 offset0:7 offset1:8
	ds_read2_b32 v[62:63], v50 offset0:9 offset1:10
	ds_read2_b32 v[64:65], v50 offset0:11 offset1:12
	ds_read2_b32 v[66:67], v50 offset0:13 offset1:14
	ds_read2_b32 v[68:69], v50 offset0:15 offset1:16
	ds_read2_b32 v[70:71], v50 offset0:17 offset1:18
	ds_read2_b32 v[72:73], v50 offset0:19 offset1:20
	ds_read2_b32 v[74:75], v50 offset0:21 offset1:22
	ds_read2_b32 v[76:77], v50 offset0:23 offset1:24
	ds_read2_b32 v[78:79], v50 offset0:25 offset1:26
	ds_read2_b32 v[80:81], v50 offset0:27 offset1:28
	ds_read2_b32 v[234:235], v50 offset0:29 offset1:30
	v_mov_b32_e32 v240, s38
	v_mov_b32_e32 v238, -2.0
	s_waitcnt lgkmcnt(0)
	v_cmp_ge_u32_e64 vcc, 3, v240
	v_cmp_ge_u32_e64 s[0:1], 4, v240
	v_cmp_ge_u32_e64 s[40:41], 5, v240
	v_cndmask_b32_e64 v54, v54, v238, vcc
	v_cmp_ge_u32_e64 vcc, 6, v240
	v_cndmask_b32_e64 v55, v55, v238, s[0:1]
	v_cmp_ge_u32_e64 s[0:1], 7, v240
	v_cndmask_b32_e64 v56, v56, v238, s[40:41]
	v_cmp_ge_u32_e64 s[40:41], 8, v240
	v_cndmask_b32_e64 v57, v57, v238, vcc
	v_cmp_ge_u32_e64 vcc, 9, v240
	v_cndmask_b32_e64 v58, v58, v238, s[0:1]
	v_cmp_ge_u32_e64 s[0:1], 10, v240
	v_cndmask_b32_e64 v59, v59, v238, s[40:41]
	v_cmp_ge_u32_e64 s[40:41], 11, v240
	v_cndmask_b32_e64 v60, v60, v238, vcc
	v_cmp_ge_u32_e64 vcc, 12, v240
	v_cndmask_b32_e64 v61, v61, v238, s[0:1]
	v_cmp_ge_u32_e64 s[0:1], 13, v240
	v_cndmask_b32_e64 v62, v62, v238, s[40:41]
	v_cmp_ge_u32_e64 s[40:41], 14, v240
	v_cndmask_b32_e64 v63, v63, v238, vcc
	v_cmp_ge_u32_e64 vcc, 15, v240
	v_cndmask_b32_e64 v64, v64, v238, s[0:1]
	v_cmp_ge_u32_e64 s[0:1], 16, v240
	v_cndmask_b32_e64 v65, v65, v238, s[40:41]
	v_cmp_ge_u32_e64 s[40:41], 17, v240
	v_cndmask_b32_e64 v66, v66, v238, vcc
	v_cmp_ge_u32_e64 vcc, 18, v240
	v_cndmask_b32_e64 v67, v67, v238, s[0:1]
	v_cmp_ge_u32_e64 s[0:1], 19, v240
	v_cndmask_b32_e64 v68, v68, v238, s[40:41]
	v_cmp_ge_u32_e64 s[40:41], 20, v240
	v_cndmask_b32_e64 v69, v69, v238, vcc
	v_cmp_ge_u32_e64 vcc, 21, v240
	v_cndmask_b32_e64 v70, v70, v238, s[0:1]
	v_cmp_ge_u32_e64 s[0:1], 22, v240
	v_cndmask_b32_e64 v71, v71, v238, s[40:41]
	v_cmp_ge_u32_e64 s[40:41], 23, v240
	v_cndmask_b32_e64 v72, v72, v238, vcc
	v_cmp_ge_u32_e64 vcc, 24, v240
	v_cndmask_b32_e64 v73, v73, v238, s[0:1]
	v_cmp_ge_u32_e64 s[0:1], 25, v240
	v_cndmask_b32_e64 v74, v74, v238, s[40:41]
	v_cmp_ge_u32_e64 s[40:41], 26, v240
	v_cndmask_b32_e64 v75, v75, v238, vcc
	v_cmp_ge_u32_e64 vcc, 27, v240
	v_cndmask_b32_e64 v76, v76, v238, s[0:1]
	v_cmp_ge_u32_e64 s[0:1], 28, v240
	v_cndmask_b32_e64 v77, v77, v238, s[40:41]
	v_cmp_ge_u32_e64 s[40:41], 29, v240
	v_cndmask_b32_e64 v78, v78, v238, vcc
	v_cmp_ge_u32_e64 vcc, 30, v240
	v_cndmask_b32_e64 v79, v79, v238, s[0:1]
	v_cmp_ge_u32_e64 s[0:1], 31, v240
	v_cndmask_b32_e64 v80, v80, v238, s[40:41]
	s_nop 0
	v_cndmask_b32_e64 v81, v81, v238, vcc
	s_nop 0
	v_cndmask_b32_e64 v234, v234, v238, s[0:1]
	v_mov_b32_e32 v236, -1.0
	v_mov_b32_e32 v237, -1
	v_cmp_gt_f32_e32 vcc, v54, v236
	s_nop 1
	v_cndmask_b32_e32 v236, v236, v54, vcc
	v_cndmask_b32_e64 v237, v237, 1, vcc
	v_cmp_gt_f32_e32 vcc, v55, v236
	s_nop 1
	v_cndmask_b32_e32 v236, v236, v55, vcc
	v_cndmask_b32_e64 v237, v237, 2, vcc
	v_cmp_gt_f32_e32 vcc, v56, v236
	s_nop 1
	v_cndmask_b32_e32 v236, v236, v56, vcc
	v_cndmask_b32_e64 v237, v237, 3, vcc
	v_cmp_gt_f32_e32 vcc, v57, v236
	s_nop 1
	v_cndmask_b32_e32 v236, v236, v57, vcc
	v_cndmask_b32_e64 v237, v237, 4, vcc
	v_cmp_gt_f32_e32 vcc, v58, v236
	s_nop 1
	v_cndmask_b32_e32 v236, v236, v58, vcc
	v_cndmask_b32_e64 v237, v237, 5, vcc
	v_cmp_gt_f32_e32 vcc, v59, v236
	s_nop 1
	v_cndmask_b32_e32 v236, v236, v59, vcc
	v_cndmask_b32_e64 v237, v237, 6, vcc
	v_cmp_gt_f32_e32 vcc, v60, v236
	s_nop 1
	v_cndmask_b32_e32 v236, v236, v60, vcc
	v_cndmask_b32_e64 v237, v237, 7, vcc
	v_cmp_gt_f32_e32 vcc, v61, v236
	s_nop 1
	v_cndmask_b32_e32 v236, v236, v61, vcc
	v_cndmask_b32_e64 v237, v237, 8, vcc
	v_cmp_gt_f32_e32 vcc, v62, v236
	s_nop 1
	v_cndmask_b32_e32 v236, v236, v62, vcc
	v_cndmask_b32_e64 v237, v237, 9, vcc
	v_cmp_gt_f32_e32 vcc, v63, v236
	s_nop 1
	v_cndmask_b32_e32 v236, v236, v63, vcc
	v_cndmask_b32_e64 v237, v237, 10, vcc
	v_cmp_gt_f32_e32 vcc, v64, v236
	s_nop 1
	v_cndmask_b32_e32 v236, v236, v64, vcc
	v_cndmask_b32_e64 v237, v237, 11, vcc
	v_cmp_gt_f32_e32 vcc, v65, v236
	s_nop 1
	v_cndmask_b32_e32 v236, v236, v65, vcc
	v_cndmask_b32_e64 v237, v237, 12, vcc
	v_cmp_gt_f32_e32 vcc, v66, v236
	s_nop 1
	v_cndmask_b32_e32 v236, v236, v66, vcc
	v_cndmask_b32_e64 v237, v237, 13, vcc
	v_cmp_gt_f32_e32 vcc, v67, v236
	s_nop 1
	v_cndmask_b32_e32 v236, v236, v67, vcc
	v_cndmask_b32_e64 v237, v237, 14, vcc
	v_cmp_gt_f32_e32 vcc, v68, v236
	s_nop 1
	v_cndmask_b32_e32 v236, v236, v68, vcc
	v_cndmask_b32_e64 v237, v237, 15, vcc
	v_cmp_gt_f32_e32 vcc, v69, v236
	s_nop 1
	v_cndmask_b32_e32 v236, v236, v69, vcc
	v_cndmask_b32_e64 v237, v237, 16, vcc
	v_cmp_gt_f32_e32 vcc, v70, v236
	s_nop 1
	v_cndmask_b32_e32 v236, v236, v70, vcc
	v_cndmask_b32_e64 v237, v237, 17, vcc
	v_cmp_gt_f32_e32 vcc, v71, v236
	s_nop 1
	v_cndmask_b32_e32 v236, v236, v71, vcc
	v_cndmask_b32_e64 v237, v237, 18, vcc
	v_cmp_gt_f32_e32 vcc, v72, v236
	s_nop 1
	v_cndmask_b32_e32 v236, v236, v72, vcc
	v_cndmask_b32_e64 v237, v237, 19, vcc
	v_cmp_gt_f32_e32 vcc, v73, v236
	s_nop 1
	v_cndmask_b32_e32 v236, v236, v73, vcc
; DEVI void nsa_item(const Params& p, int l, int item, char* lds_raw, volatile int* nsa_cnt) {
;     ...
;     while (cnt < 8) {
;       int best = -1;
;       float bv = -1.f;
;       for (int J = 0; J <= cur; ++J) {
;         float v = Pb[tid * 33 + J];
;         if (!((sel >> J) & 1u) && v > bv) { bv = v; best = J; }
;       }
;       if (best < 0) break;
;       sel |= 1u << best;
;       ++cnt;
;     }
	v_cndmask_b32_e64 v237, v237, 20, vcc
	v_cmp_gt_f32_e32 vcc, v74, v236
	s_nop 1
	v_cndmask_b32_e32 v236, v236, v74, vcc
	v_cndmask_b32_e64 v237, v237, 21, vcc
	v_cmp_gt_f32_e32 vcc, v75, v236
	s_nop 1
	v_cndmask_b32_e32 v236, v236, v75, vcc
	v_cndmask_b32_e64 v237, v237, 22, vcc
	v_cmp_gt_f32_e32 vcc, v76, v236
	s_nop 1
	v_cndmask_b32_e32 v236, v236, v76, vcc
	v_cndmask_b32_e64 v237, v237, 23, vcc
	v_cmp_gt_f32_e32 vcc, v77, v236
	s_nop 1
	v_cndmask_b32_e32 v236, v236, v77, vcc
	v_cndmask_b32_e64 v237, v237, 24, vcc
	v_cmp_gt_f32_e32 vcc, v78, v236
	s_nop 1
	v_cndmask_b32_e32 v236, v236, v78, vcc
	v_cndmask_b32_e64 v237, v237, 25, vcc
	v_cmp_gt_f32_e32 vcc, v79, v236
	s_nop 1
	v_cndmask_b32_e32 v236, v236, v79, vcc
	v_cndmask_b32_e64 v237, v237, 26, vcc
	v_cmp_gt_f32_e32 vcc, v80, v236
	s_nop 1
	v_cndmask_b32_e32 v236, v236, v80, vcc
	v_cndmask_b32_e64 v237, v237, 27, vcc
	v_cmp_gt_f32_e32 vcc, v81, v236
	s_nop 1
	v_cndmask_b32_e32 v236, v236, v81, vcc
	v_cndmask_b32_e64 v237, v237, 28, vcc
	v_cmp_gt_f32_e32 vcc, v234, v236
	s_nop 1
	v_cndmask_b32_e32 v236, v236, v234, vcc
	v_cndmask_b32_e64 v237, v237, 29, vcc
	v_cmp_le_i32_e32 vcc, 0, v237
	v_lshlrev_b32_e32 v239, v237, v224
	s_nop 0
	v_cndmask_b32_e32 v239, 0, v239, vcc
	v_or_b32_e32 v51, v51, v239
	v_cmp_eq_u32_e64 vcc, 1, v237
	v_cmp_eq_u32_e64 s[0:1], 2, v237
	v_cmp_eq_u32_e64 s[40:41], 3, v237
	v_cndmask_b32_e64 v54, v54, v238, vcc
	v_cmp_eq_u32_e64 vcc, 4, v237
	v_cndmask_b32_e64 v55, v55, v238, s[0:1]
	v_cmp_eq_u32_e64 s[0:1], 5, v237
	v_cndmask_b32_e64 v56, v56, v238, s[40:41]
	v_cmp_eq_u32_e64 s[40:41], 6, v237
	v_cndmask_b32_e64 v57, v57, v238, vcc
	v_cmp_eq_u32_e64 vcc, 7, v237
	v_cndmask_b32_e64 v58, v58, v238, s[0:1]
	v_cmp_eq_u32_e64 s[0:1], 8, v237
	v_cndmask_b32_e64 v59, v59, v238, s[40:41]
	v_cmp_eq_u32_e64 s[40:41], 9, v237
	v_cndmask_b32_e64 v60, v60, v238, vcc
	v_cmp_eq_u32_e64 vcc, 10, v237
	v_cndmask_b32_e64 v61, v61, v238, s[0:1]
	v_cmp_eq_u32_e64 s[0:1], 11, v237
	v_cndmask_b32_e64 v62, v62, v238, s[40:41]
	v_cmp_eq_u32_e64 s[40:41], 12, v237
	v_cndmask_b32_e64 v63, v63, v238, vcc
	v_cmp_eq_u32_e64 vcc, 13, v237
	v_cndmask_b32_e64 v64, v64, v238, s[0:1]
	v_cmp_eq_u32_e64 s[0:1], 14, v237
	v_cndmask_b32_e64 v65, v65, v238, s[40:41]
	v_cmp_eq_u32_e64 s[40:41], 15, v237
	v_cndmask_b32_e64 v66, v66, v238, vcc
	v_cmp_eq_u32_e64 vcc, 16, v237
	v_cndmask_b32_e64 v67, v67, v238, s[0:1]
	v_cmp_eq_u32_e64 s[0:1], 17, v237
	v_cndmask_b32_e64 v68, v68, v238, s[40:41]
	v_cmp_eq_u32_e64 s[40:41], 18, v237
	v_cndmask_b32_e64 v69, v69, v238, vcc
	v_cmp_eq_u32_e64 vcc, 19, v237
	v_cndmask_b32_e64 v70, v70, v238, s[0:1]
	v_cmp_eq_u32_e64 s[0:1], 20, v237
	v_cndmask_b32_e64 v71, v71, v238, s[40:41]
	v_cmp_eq_u32_e64 s[40:41], 21, v237
	v_cndmask_b32_e64 v72, v72, v238, vcc
	v_cmp_eq_u32_e64 vcc, 22, v237
	v_cndmask_b32_e64 v73, v73, v238, s[0:1]
	v_cmp_eq_u32_e64 s[0:1], 23, v237
	v_cndmask_b32_e64 v74, v74, v238, s[40:41]
	v_cmp_eq_u32_e64 s[40:41], 24, v237
	v_cndmask_b32_e64 v75, v75, v238, vcc
	v_cmp_eq_u32_e64 vcc, 25, v237
	v_cndmask_b32_e64 v76, v76, v238, s[0:1]
	v_cmp_eq_u32_e64 s[0:1], 26, v237
	v_cndmask_b32_e64 v77, v77, v238, s[40:41]
	v_cmp_eq_u32_e64 s[40:41], 27, v237
	v_cndmask_b32_e64 v78, v78, v238, vcc
	v_cmp_eq_u32_e64 vcc, 28, v237
	v_cndmask_b32_e64 v79, v79, v238, s[0:1]
	v_cmp_eq_u32_e64 s[0:1], 29, v237
	v_cndmask_b32_e64 v80, v80, v238, s[40:41]
	s_nop 0
	v_cndmask_b32_e64 v81, v81, v238, vcc
	s_nop 0
	v_cndmask_b32_e64 v234, v234, v238, s[0:1]
	v_mov_b32_e32 v236, -1.0
	v_mov_b32_e32 v237, -1
	v_cmp_gt_f32_e32 vcc, v54, v236
	s_nop 1
	v_cndmask_b32_e32 v236, v236, v54, vcc
	v_cndmask_b32_e64 v237, v237, 1, vcc
	v_cmp_gt_f32_e32 vcc, v55, v236
	s_nop 1
	v_cndmask_b32_e32 v236, v236, v55, vcc
	v_cndmask_b32_e64 v237, v237, 2, vcc
	v_cmp_gt_f32_e32 vcc, v56, v236
	s_nop 1
	v_cndmask_b32_e32 v236, v236, v56, vcc
	v_cndmask_b32_e64 v237, v237, 3, vcc
	v_cmp_gt_f32_e32 vcc, v57, v236
	s_nop 1
	v_cndmask_b32_e32 v236, v236, v57, vcc
	v_cndmask_b32_e64 v237, v237, 4, vcc
	v_cmp_gt_f32_e32 vcc, v58, v236
	s_nop 1
	v_cndmask_b32_e32 v236, v236, v58, vcc
	v_cndmask_b32_e64 v237, v237, 5, vcc
	v_cmp_gt_f32_e32 vcc, v59, v236
	s_nop 1
	v_cndmask_b32_e32 v236, v236, v59, vcc
	v_cndmask_b32_e64 v237, v237, 6, vcc
	v_cmp_gt_f32_e32 vcc, v60, v236
	s_nop 1
	v_cndmask_b32_e32 v236, v236, v60, vcc
	v_cndmask_b32_e64 v237, v237, 7, vcc
	v_cmp_gt_f32_e32 vcc, v61, v236
	s_nop 1
	v_cndmask_b32_e32 v236, v236, v61, vcc
	v_cndmask_b32_e64 v237, v237, 8, vcc
	v_cmp_gt_f32_e32 vcc, v62, v236
	s_nop 1
	v_cndmask_b32_e32 v236, v236, v62, vcc
	v_cndmask_b32_e64 v237, v237, 9, vcc
	v_cmp_gt_f32_e32 vcc, v63, v236
	s_nop 1
	v_cndmask_b32_e32 v236, v236, v63, vcc
	v_cndmask_b32_e64 v237, v237, 10, vcc
	v_cmp_gt_f32_e32 vcc, v64, v236
	s_nop 1
	v_cndmask_b32_e32 v236, v236, v64, vcc
	v_cndmask_b32_e64 v237, v237, 11, vcc
	v_cmp_gt_f32_e32 vcc, v65, v236
	s_nop 1
	v_cndmask_b32_e32 v236, v236, v65, vcc
	v_cndmask_b32_e64 v237, v237, 12, vcc
	v_cmp_gt_f32_e32 vcc, v66, v236
	s_nop 1
	v_cndmask_b32_e32 v236, v236, v66, vcc
	v_cndmask_b32_e64 v237, v237, 13, vcc
	v_cmp_gt_f32_e32 vcc, v67, v236
	s_nop 1
	v_cndmask_b32_e32 v236, v236, v67, vcc
	v_cndmask_b32_e64 v237, v237, 14, vcc
	v_cmp_gt_f32_e32 vcc, v68, v236
	s_nop 1
	v_cndmask_b32_e32 v236, v236, v68, vcc
	v_cndmask_b32_e64 v237, v237, 15, vcc
	v_cmp_gt_f32_e32 vcc, v69, v236
	s_nop 1
	v_cndmask_b32_e32 v236, v236, v69, vcc
	v_cndmask_b32_e64 v237, v237, 16, vcc
	v_cmp_gt_f32_e32 vcc, v70, v236
	s_nop 1
	v_cndmask_b32_e32 v236, v236, v70, vcc
	v_cndmask_b32_e64 v237, v237, 17, vcc
	v_cmp_gt_f32_e32 vcc, v71, v236
	s_nop 1
; DEVI void nsa_item(const Params& p, int l, int item, char* lds_raw, volatile int* nsa_cnt) {
;     ...
;     while (cnt < 8) {
;       int best = -1;
;       float bv = -1.f;
;       for (int J = 0; J <= cur; ++J) {
;         float v = Pb[tid * 33 + J];
;         if (!((sel >> J) & 1u) && v > bv) { bv = v; best = J; }
;       }
;       if (best < 0) break;
;       sel |= 1u << best;
;       ++cnt;
;     }
	v_cndmask_b32_e32 v236, v236, v71, vcc
	v_cndmask_b32_e64 v237, v237, 18, vcc
	v_cmp_gt_f32_e32 vcc, v72, v236
	s_nop 1
	v_cndmask_b32_e32 v236, v236, v72, vcc
	v_cndmask_b32_e64 v237, v237, 19, vcc
	v_cmp_gt_f32_e32 vcc, v73, v236
	s_nop 1
	v_cndmask_b32_e32 v236, v236, v73, vcc
	v_cndmask_b32_e64 v237, v237, 20, vcc
	v_cmp_gt_f32_e32 vcc, v74, v236
	s_nop 1
	v_cndmask_b32_e32 v236, v236, v74, vcc
	v_cndmask_b32_e64 v237, v237, 21, vcc
	v_cmp_gt_f32_e32 vcc, v75, v236
	s_nop 1
	v_cndmask_b32_e32 v236, v236, v75, vcc
	v_cndmask_b32_e64 v237, v237, 22, vcc
	v_cmp_gt_f32_e32 vcc, v76, v236
	s_nop 1
	v_cndmask_b32_e32 v236, v236, v76, vcc
	v_cndmask_b32_e64 v237, v237, 23, vcc
	v_cmp_gt_f32_e32 vcc, v77, v236
	s_nop 1
	v_cndmask_b32_e32 v236, v236, v77, vcc
	v_cndmask_b32_e64 v237, v237, 24, vcc
	v_cmp_gt_f32_e32 vcc, v78, v236
	s_nop 1
	v_cndmask_b32_e32 v236, v236, v78, vcc
	v_cndmask_b32_e64 v237, v237, 25, vcc
	v_cmp_gt_f32_e32 vcc, v79, v236
	s_nop 1
	v_cndmask_b32_e32 v236, v236, v79, vcc
	v_cndmask_b32_e64 v237, v237, 26, vcc
	v_cmp_gt_f32_e32 vcc, v80, v236
	s_nop 1
	v_cndmask_b32_e32 v236, v236, v80, vcc
	v_cndmask_b32_e64 v237, v237, 27, vcc
	v_cmp_gt_f32_e32 vcc, v81, v236
	s_nop 1
	v_cndmask_b32_e32 v236, v236, v81, vcc
	v_cndmask_b32_e64 v237, v237, 28, vcc
	v_cmp_gt_f32_e32 vcc, v234, v236
	s_nop 1
	v_cndmask_b32_e32 v236, v236, v234, vcc
	v_cndmask_b32_e64 v237, v237, 29, vcc
	v_cmp_le_i32_e32 vcc, 0, v237
	v_lshlrev_b32_e32 v239, v237, v224
	s_nop 0
	v_cndmask_b32_e32 v239, 0, v239, vcc
	v_or_b32_e32 v51, v51, v239
	v_cmp_eq_u32_e64 vcc, 1, v237
	v_cmp_eq_u32_e64 s[0:1], 2, v237
	v_cmp_eq_u32_e64 s[40:41], 3, v237
	v_cndmask_b32_e64 v54, v54, v238, vcc
	v_cmp_eq_u32_e64 vcc, 4, v237
	v_cndmask_b32_e64 v55, v55, v238, s[0:1]
	v_cmp_eq_u32_e64 s[0:1], 5, v237
	v_cndmask_b32_e64 v56, v56, v238, s[40:41]
	v_cmp_eq_u32_e64 s[40:41], 6, v237
	v_cndmask_b32_e64 v57, v57, v238, vcc
	v_cmp_eq_u32_e64 vcc, 7, v237
	v_cndmask_b32_e64 v58, v58, v238, s[0:1]
	v_cmp_eq_u32_e64 s[0:1], 8, v237
	v_cndmask_b32_e64 v59, v59, v238, s[40:41]
	v_cmp_eq_u32_e64 s[40:41], 9, v237
	v_cndmask_b32_e64 v60, v60, v238, vcc
	v_cmp_eq_u32_e64 vcc, 10, v237
	v_cndmask_b32_e64 v61, v61, v238, s[0:1]
	v_cmp_eq_u32_e64 s[0:1], 11, v237
	v_cndmask_b32_e64 v62, v62, v238, s[40:41]
	v_cmp_eq_u32_e64 s[40:41], 12, v237
	v_cndmask_b32_e64 v63, v63, v238, vcc
	v_cmp_eq_u32_e64 vcc, 13, v237
	v_cndmask_b32_e64 v64, v64, v238, s[0:1]
	v_cmp_eq_u32_e64 s[0:1], 14, v237
	v_cndmask_b32_e64 v65, v65, v238, s[40:41]
	v_cmp_eq_u32_e64 s[40:41], 15, v237
	v_cndmask_b32_e64 v66, v66, v238, vcc
	v_cmp_eq_u32_e64 vcc, 16, v237
	v_cndmask_b32_e64 v67, v67, v238, s[0:1]
	v_cmp_eq_u32_e64 s[0:1], 17, v237
	v_cndmask_b32_e64 v68, v68, v238, s[40:41]
	v_cmp_eq_u32_e64 s[40:41], 18, v237
	v_cndmask_b32_e64 v69, v69, v238, vcc
	v_cmp_eq_u32_e64 vcc, 19, v237
	v_cndmask_b32_e64 v70, v70, v238, s[0:1]
	v_cmp_eq_u32_e64 s[0:1], 20, v237
	v_cndmask_b32_e64 v71, v71, v238, s[40:41]
	v_cmp_eq_u32_e64 s[40:41], 21, v237
	v_cndmask_b32_e64 v72, v72, v238, vcc
	v_cmp_eq_u32_e64 vcc, 22, v237
	v_cndmask_b32_e64 v73, v73, v238, s[0:1]
	v_cmp_eq_u32_e64 s[0:1], 23, v237
	v_cndmask_b32_e64 v74, v74, v238, s[40:41]
	v_cmp_eq_u32_e64 s[40:41], 24, v237
	v_cndmask_b32_e64 v75, v75, v238, vcc
	v_cmp_eq_u32_e64 vcc, 25, v237
	v_cndmask_b32_e64 v76, v76, v238, s[0:1]
	v_cmp_eq_u32_e64 s[0:1], 26, v237
	v_cndmask_b32_e64 v77, v77, v238, s[40:41]
	v_cmp_eq_u32_e64 s[40:41], 27, v237
	v_cndmask_b32_e64 v78, v78, v238, vcc
	v_cmp_eq_u32_e64 vcc, 28, v237
	v_cndmask_b32_e64 v79, v79, v238, s[0:1]
	v_cmp_eq_u32_e64 s[0:1], 29, v237
	v_cndmask_b32_e64 v80, v80, v238, s[40:41]
	s_nop 0
	v_cndmask_b32_e64 v81, v81, v238, vcc
	s_nop 0
	v_cndmask_b32_e64 v234, v234, v238, s[0:1]
	v_mov_b32_e32 v236, -1.0
	v_mov_b32_e32 v237, -1
	v_cmp_gt_f32_e32 vcc, v54, v236
	s_nop 1
	v_cndmask_b32_e32 v236, v236, v54, vcc
	v_cndmask_b32_e64 v237, v237, 1, vcc
	v_cmp_gt_f32_e32 vcc, v55, v236
	s_nop 1
	v_cndmask_b32_e32 v236, v236, v55, vcc
	v_cndmask_b32_e64 v237, v237, 2, vcc
	v_cmp_gt_f32_e32 vcc, v56, v236
	s_nop 1
	v_cndmask_b32_e32 v236, v236, v56, vcc
	v_cndmask_b32_e64 v237, v237, 3, vcc
	v_cmp_gt_f32_e32 vcc, v57, v236
	s_nop 1
	v_cndmask_b32_e32 v236, v236, v57, vcc
	v_cndmask_b32_e64 v237, v237, 4, vcc
	v_cmp_gt_f32_e32 vcc, v58, v236
	s_nop 1
	v_cndmask_b32_e32 v236, v236, v58, vcc
	v_cndmask_b32_e64 v237, v237, 5, vcc
	v_cmp_gt_f32_e32 vcc, v59, v236
	s_nop 1
	v_cndmask_b32_e32 v236, v236, v59, vcc
	v_cndmask_b32_e64 v237, v237, 6, vcc
	v_cmp_gt_f32_e32 vcc, v60, v236
	s_nop 1
	v_cndmask_b32_e32 v236, v236, v60, vcc
	v_cndmask_b32_e64 v237, v237, 7, vcc
	v_cmp_gt_f32_e32 vcc, v61, v236
	s_nop 1
	v_cndmask_b32_e32 v236, v236, v61, vcc
	v_cndmask_b32_e64 v237, v237, 8, vcc
	v_cmp_gt_f32_e32 vcc, v62, v236
	s_nop 1
	v_cndmask_b32_e32 v236, v236, v62, vcc
	v_cndmask_b32_e64 v237, v237, 9, vcc
	v_cmp_gt_f32_e32 vcc, v63, v236
	s_nop 1
	v_cndmask_b32_e32 v236, v236, v63, vcc
	v_cndmask_b32_e64 v237, v237, 10, vcc
	v_cmp_gt_f32_e32 vcc, v64, v236
	s_nop 1
	v_cndmask_b32_e32 v236, v236, v64, vcc
	v_cndmask_b32_e64 v237, v237, 11, vcc
	v_cmp_gt_f32_e32 vcc, v65, v236
	s_nop 1
	v_cndmask_b32_e32 v236, v236, v65, vcc
	v_cndmask_b32_e64 v237, v237, 12, vcc
	v_cmp_gt_f32_e32 vcc, v66, v236
	s_nop 1
	v_cndmask_b32_e32 v236, v236, v66, vcc
	v_cndmask_b32_e64 v237, v237, 13, vcc
	v_cmp_gt_f32_e32 vcc, v67, v236
	s_nop 1
	v_cndmask_b32_e32 v236, v236, v67, vcc
	v_cndmask_b32_e64 v237, v237, 14, vcc
	v_cmp_gt_f32_e32 vcc, v68, v236
	s_nop 1
	v_cndmask_b32_e32 v236, v236, v68, vcc
	v_cndmask_b32_e64 v237, v237, 15, vcc
; DEVI void nsa_item(const Params& p, int l, int item, char* lds_raw, volatile int* nsa_cnt) {
;     ...
;     while (cnt < 8) {
;       int best = -1;
;       float bv = -1.f;
;       for (int J = 0; J <= cur; ++J) {
;         float v = Pb[tid * 33 + J];
;         if (!((sel >> J) & 1u) && v > bv) { bv = v; best = J; }
;       }
;       if (best < 0) break;
;       sel |= 1u << best;
;       ++cnt;
;     }
	v_cmp_gt_f32_e32 vcc, v69, v236
	s_nop 1
	v_cndmask_b32_e32 v236, v236, v69, vcc
	v_cndmask_b32_e64 v237, v237, 16, vcc
	v_cmp_gt_f32_e32 vcc, v70, v236
	s_nop 1
	v_cndmask_b32_e32 v236, v236, v70, vcc
	v_cndmask_b32_e64 v237, v237, 17, vcc
	v_cmp_gt_f32_e32 vcc, v71, v236
	s_nop 1
	v_cndmask_b32_e32 v236, v236, v71, vcc
	v_cndmask_b32_e64 v237, v237, 18, vcc
	v_cmp_gt_f32_e32 vcc, v72, v236
	s_nop 1
	v_cndmask_b32_e32 v236, v236, v72, vcc
	v_cndmask_b32_e64 v237, v237, 19, vcc
	v_cmp_gt_f32_e32 vcc, v73, v236
	s_nop 1
	v_cndmask_b32_e32 v236, v236, v73, vcc
	v_cndmask_b32_e64 v237, v237, 20, vcc
	v_cmp_gt_f32_e32 vcc, v74, v236
	s_nop 1
	v_cndmask_b32_e32 v236, v236, v74, vcc
	v_cndmask_b32_e64 v237, v237, 21, vcc
	v_cmp_gt_f32_e32 vcc, v75, v236
	s_nop 1
	v_cndmask_b32_e32 v236, v236, v75, vcc
	v_cndmask_b32_e64 v237, v237, 22, vcc
	v_cmp_gt_f32_e32 vcc, v76, v236
	s_nop 1
	v_cndmask_b32_e32 v236, v236, v76, vcc
	v_cndmask_b32_e64 v237, v237, 23, vcc
	v_cmp_gt_f32_e32 vcc, v77, v236
	s_nop 1
	v_cndmask_b32_e32 v236, v236, v77, vcc
	v_cndmask_b32_e64 v237, v237, 24, vcc
	v_cmp_gt_f32_e32 vcc, v78, v236
	s_nop 1
	v_cndmask_b32_e32 v236, v236, v78, vcc
	v_cndmask_b32_e64 v237, v237, 25, vcc
	v_cmp_gt_f32_e32 vcc, v79, v236
	s_nop 1
	v_cndmask_b32_e32 v236, v236, v79, vcc
	v_cndmask_b32_e64 v237, v237, 26, vcc
	v_cmp_gt_f32_e32 vcc, v80, v236
	s_nop 1
	v_cndmask_b32_e32 v236, v236, v80, vcc
	v_cndmask_b32_e64 v237, v237, 27, vcc
	v_cmp_gt_f32_e32 vcc, v81, v236
	s_nop 1
	v_cndmask_b32_e32 v236, v236, v81, vcc
	v_cndmask_b32_e64 v237, v237, 28, vcc
	v_cmp_gt_f32_e32 vcc, v234, v236
	s_nop 1
	v_cndmask_b32_e32 v236, v236, v234, vcc
	v_cndmask_b32_e64 v237, v237, 29, vcc
	v_cmp_le_i32_e32 vcc, 0, v237
	v_lshlrev_b32_e32 v239, v237, v224
	s_nop 0
	v_cndmask_b32_e32 v239, 0, v239, vcc
	v_or_b32_e32 v51, v51, v239
	v_cmp_eq_u32_e64 vcc, 1, v237
	v_cmp_eq_u32_e64 s[0:1], 2, v237
	v_cmp_eq_u32_e64 s[40:41], 3, v237
	v_cndmask_b32_e64 v54, v54, v238, vcc
	v_cmp_eq_u32_e64 vcc, 4, v237
	v_cndmask_b32_e64 v55, v55, v238, s[0:1]
	v_cmp_eq_u32_e64 s[0:1], 5, v237
	v_cndmask_b32_e64 v56, v56, v238, s[40:41]
	v_cmp_eq_u32_e64 s[40:41], 6, v237
	v_cndmask_b32_e64 v57, v57, v238, vcc
	v_cmp_eq_u32_e64 vcc, 7, v237
	v_cndmask_b32_e64 v58, v58, v238, s[0:1]
	v_cmp_eq_u32_e64 s[0:1], 8, v237
	v_cndmask_b32_e64 v59, v59, v238, s[40:41]
	v_cmp_eq_u32_e64 s[40:41], 9, v237
	v_cndmask_b32_e64 v60, v60, v238, vcc
	v_cmp_eq_u32_e64 vcc, 10, v237
	v_cndmask_b32_e64 v61, v61, v238, s[0:1]
	v_cmp_eq_u32_e64 s[0:1], 11, v237
	v_cndmask_b32_e64 v62, v62, v238, s[40:41]
	v_cmp_eq_u32_e64 s[40:41], 12, v237
	v_cndmask_b32_e64 v63, v63, v238, vcc
	v_cmp_eq_u32_e64 vcc, 13, v237
	v_cndmask_b32_e64 v64, v64, v238, s[0:1]
	v_cmp_eq_u32_e64 s[0:1], 14, v237
	v_cndmask_b32_e64 v65, v65, v238, s[40:41]
	v_cmp_eq_u32_e64 s[40:41], 15, v237
	v_cndmask_b32_e64 v66, v66, v238, vcc
	v_cmp_eq_u32_e64 vcc, 16, v237
	v_cndmask_b32_e64 v67, v67, v238, s[0:1]
	v_cmp_eq_u32_e64 s[0:1], 17, v237
	v_cndmask_b32_e64 v68, v68, v238, s[40:41]
	v_cmp_eq_u32_e64 s[40:41], 18, v237
	v_cndmask_b32_e64 v69, v69, v238, vcc
	v_cmp_eq_u32_e64 vcc, 19, v237
	v_cndmask_b32_e64 v70, v70, v238, s[0:1]
	v_cmp_eq_u32_e64 s[0:1], 20, v237
	v_cndmask_b32_e64 v71, v71, v238, s[40:41]
	v_cmp_eq_u32_e64 s[40:41], 21, v237
	v_cndmask_b32_e64 v72, v72, v238, vcc
	v_cmp_eq_u32_e64 vcc, 22, v237
	v_cndmask_b32_e64 v73, v73, v238, s[0:1]
	v_cmp_eq_u32_e64 s[0:1], 23, v237
	v_cndmask_b32_e64 v74, v74, v238, s[40:41]
	v_cmp_eq_u32_e64 s[40:41], 24, v237
	v_cndmask_b32_e64 v75, v75, v238, vcc
	v_cmp_eq_u32_e64 vcc, 25, v237
	v_cndmask_b32_e64 v76, v76, v238, s[0:1]
	v_cmp_eq_u32_e64 s[0:1], 26, v237
	v_cndmask_b32_e64 v77, v77, v238, s[40:41]
	v_cmp_eq_u32_e64 s[40:41], 27, v237
	v_cndmask_b32_e64 v78, v78, v238, vcc
	v_cmp_eq_u32_e64 vcc, 28, v237
	v_cndmask_b32_e64 v79, v79, v238, s[0:1]
	v_cmp_eq_u32_e64 s[0:1], 29, v237
	v_cndmask_b32_e64 v80, v80, v238, s[40:41]
	s_nop 0
	v_cndmask_b32_e64 v81, v81, v238, vcc
	s_nop 0
	v_cndmask_b32_e64 v234, v234, v238, s[0:1]
	v_mov_b32_e32 v236, -1.0
	v_mov_b32_e32 v237, -1
	v_cmp_gt_f32_e32 vcc, v54, v236
	s_nop 1
	v_cndmask_b32_e32 v236, v236, v54, vcc
	v_cndmask_b32_e64 v237, v237, 1, vcc
	v_cmp_gt_f32_e32 vcc, v55, v236
	s_nop 1
	v_cndmask_b32_e32 v236, v236, v55, vcc
	v_cndmask_b32_e64 v237, v237, 2, vcc
	v_cmp_gt_f32_e32 vcc, v56, v236
	s_nop 1
	v_cndmask_b32_e32 v236, v236, v56, vcc
	v_cndmask_b32_e64 v237, v237, 3, vcc
	v_cmp_gt_f32_e32 vcc, v57, v236
	s_nop 1
	v_cndmask_b32_e32 v236, v236, v57, vcc
	v_cndmask_b32_e64 v237, v237, 4, vcc
	v_cmp_gt_f32_e32 vcc, v58, v236
	s_nop 1
	v_cndmask_b32_e32 v236, v236, v58, vcc
	v_cndmask_b32_e64 v237, v237, 5, vcc
	v_cmp_gt_f32_e32 vcc, v59, v236
	s_nop 1
	v_cndmask_b32_e32 v236, v236, v59, vcc
	v_cndmask_b32_e64 v237, v237, 6, vcc
	v_cmp_gt_f32_e32 vcc, v60, v236
	s_nop 1
	v_cndmask_b32_e32 v236, v236, v60, vcc
	v_cndmask_b32_e64 v237, v237, 7, vcc
	v_cmp_gt_f32_e32 vcc, v61, v236
	s_nop 1
	v_cndmask_b32_e32 v236, v236, v61, vcc
	v_cndmask_b32_e64 v237, v237, 8, vcc
	v_cmp_gt_f32_e32 vcc, v62, v236
	s_nop 1
	v_cndmask_b32_e32 v236, v236, v62, vcc
	v_cndmask_b32_e64 v237, v237, 9, vcc
	v_cmp_gt_f32_e32 vcc, v63, v236
	s_nop 1
	v_cndmask_b32_e32 v236, v236, v63, vcc
	v_cndmask_b32_e64 v237, v237, 10, vcc
	v_cmp_gt_f32_e32 vcc, v64, v236
	s_nop 1
	v_cndmask_b32_e32 v236, v236, v64, vcc
	v_cndmask_b32_e64 v237, v237, 11, vcc
	v_cmp_gt_f32_e32 vcc, v65, v236
	s_nop 1
	v_cndmask_b32_e32 v236, v236, v65, vcc
	v_cndmask_b32_e64 v237, v237, 12, vcc
	v_cmp_gt_f32_e32 vcc, v66, v236
	s_nop 1
	v_cndmask_b32_e32 v236, v236, v66, vcc
; DEVI void nsa_item(const Params& p, int l, int item, char* lds_raw, volatile int* nsa_cnt) {
;     ...
;     while (cnt < 8) {
;       int best = -1;
;       float bv = -1.f;
;       for (int J = 0; J <= cur; ++J) {
;         float v = Pb[tid * 33 + J];
;         if (!((sel >> J) & 1u) && v > bv) { bv = v; best = J; }
;       }
;       if (best < 0) break;
;       sel |= 1u << best;
;       ++cnt;
;     }
	v_cndmask_b32_e64 v237, v237, 13, vcc
	v_cmp_gt_f32_e32 vcc, v67, v236
	s_nop 1
	v_cndmask_b32_e32 v236, v236, v67, vcc
	v_cndmask_b32_e64 v237, v237, 14, vcc
	v_cmp_gt_f32_e32 vcc, v68, v236
	s_nop 1
	v_cndmask_b32_e32 v236, v236, v68, vcc
	v_cndmask_b32_e64 v237, v237, 15, vcc
	v_cmp_gt_f32_e32 vcc, v69, v236
	s_nop 1
	v_cndmask_b32_e32 v236, v236, v69, vcc
	v_cndmask_b32_e64 v237, v237, 16, vcc
	v_cmp_gt_f32_e32 vcc, v70, v236
	s_nop 1
	v_cndmask_b32_e32 v236, v236, v70, vcc
	v_cndmask_b32_e64 v237, v237, 17, vcc
	v_cmp_gt_f32_e32 vcc, v71, v236
	s_nop 1
	v_cndmask_b32_e32 v236, v236, v71, vcc
	v_cndmask_b32_e64 v237, v237, 18, vcc
	v_cmp_gt_f32_e32 vcc, v72, v236
	s_nop 1
	v_cndmask_b32_e32 v236, v236, v72, vcc
	v_cndmask_b32_e64 v237, v237, 19, vcc
	v_cmp_gt_f32_e32 vcc, v73, v236
	s_nop 1
	v_cndmask_b32_e32 v236, v236, v73, vcc
	v_cndmask_b32_e64 v237, v237, 20, vcc
	v_cmp_gt_f32_e32 vcc, v74, v236
	s_nop 1
	v_cndmask_b32_e32 v236, v236, v74, vcc
	v_cndmask_b32_e64 v237, v237, 21, vcc
	v_cmp_gt_f32_e32 vcc, v75, v236
	s_nop 1
	v_cndmask_b32_e32 v236, v236, v75, vcc
	v_cndmask_b32_e64 v237, v237, 22, vcc
	v_cmp_gt_f32_e32 vcc, v76, v236
	s_nop 1
	v_cndmask_b32_e32 v236, v236, v76, vcc
	v_cndmask_b32_e64 v237, v237, 23, vcc
	v_cmp_gt_f32_e32 vcc, v77, v236
	s_nop 1
	v_cndmask_b32_e32 v236, v236, v77, vcc
	v_cndmask_b32_e64 v237, v237, 24, vcc
	v_cmp_gt_f32_e32 vcc, v78, v236
	s_nop 1
	v_cndmask_b32_e32 v236, v236, v78, vcc
	v_cndmask_b32_e64 v237, v237, 25, vcc
	v_cmp_gt_f32_e32 vcc, v79, v236
	s_nop 1
	v_cndmask_b32_e32 v236, v236, v79, vcc
	v_cndmask_b32_e64 v237, v237, 26, vcc
	v_cmp_gt_f32_e32 vcc, v80, v236
	s_nop 1
	v_cndmask_b32_e32 v236, v236, v80, vcc
	v_cndmask_b32_e64 v237, v237, 27, vcc
	v_cmp_gt_f32_e32 vcc, v81, v236
	s_nop 1
	v_cndmask_b32_e32 v236, v236, v81, vcc
	v_cndmask_b32_e64 v237, v237, 28, vcc
	v_cmp_gt_f32_e32 vcc, v234, v236
	s_nop 1
	v_cndmask_b32_e32 v236, v236, v234, vcc
	v_cndmask_b32_e64 v237, v237, 29, vcc
	v_cmp_le_i32_e32 vcc, 0, v237
	v_lshlrev_b32_e32 v239, v237, v224
	s_nop 0
	v_cndmask_b32_e32 v239, 0, v239, vcc
	v_or_b32_e32 v51, v51, v239
	v_cmp_eq_u32_e64 vcc, 1, v237
	v_cmp_eq_u32_e64 s[0:1], 2, v237
	v_cmp_eq_u32_e64 s[40:41], 3, v237
	v_cndmask_b32_e64 v54, v54, v238, vcc
	v_cmp_eq_u32_e64 vcc, 4, v237
	v_cndmask_b32_e64 v55, v55, v238, s[0:1]
	v_cmp_eq_u32_e64 s[0:1], 5, v237
	v_cndmask_b32_e64 v56, v56, v238, s[40:41]
	v_cmp_eq_u32_e64 s[40:41], 6, v237
	v_cndmask_b32_e64 v57, v57, v238, vcc
	v_cmp_eq_u32_e64 vcc, 7, v237
	v_cndmask_b32_e64 v58, v58, v238, s[0:1]
	v_cmp_eq_u32_e64 s[0:1], 8, v237
	v_cndmask_b32_e64 v59, v59, v238, s[40:41]
	v_cmp_eq_u32_e64 s[40:41], 9, v237
	v_cndmask_b32_e64 v60, v60, v238, vcc
	v_cmp_eq_u32_e64 vcc, 10, v237
	v_cndmask_b32_e64 v61, v61, v238, s[0:1]
	v_cmp_eq_u32_e64 s[0:1], 11, v237
	v_cndmask_b32_e64 v62, v62, v238, s[40:41]
	v_cmp_eq_u32_e64 s[40:41], 12, v237
	v_cndmask_b32_e64 v63, v63, v238, vcc
	v_cmp_eq_u32_e64 vcc, 13, v237
	v_cndmask_b32_e64 v64, v64, v238, s[0:1]
	v_cmp_eq_u32_e64 s[0:1], 14, v237
	v_cndmask_b32_e64 v65, v65, v238, s[40:41]
	v_cmp_eq_u32_e64 s[40:41], 15, v237
	v_cndmask_b32_e64 v66, v66, v238, vcc
	v_cmp_eq_u32_e64 vcc, 16, v237
	v_cndmask_b32_e64 v67, v67, v238, s[0:1]
	v_cmp_eq_u32_e64 s[0:1], 17, v237
	v_cndmask_b32_e64 v68, v68, v238, s[40:41]
	v_cmp_eq_u32_e64 s[40:41], 18, v237
	v_cndmask_b32_e64 v69, v69, v238, vcc
	v_cmp_eq_u32_e64 vcc, 19, v237
	v_cndmask_b32_e64 v70, v70, v238, s[0:1]
	v_cmp_eq_u32_e64 s[0:1], 20, v237
	v_cndmask_b32_e64 v71, v71, v238, s[40:41]
	v_cmp_eq_u32_e64 s[40:41], 21, v237
	v_cndmask_b32_e64 v72, v72, v238, vcc
	v_cmp_eq_u32_e64 vcc, 22, v237
	v_cndmask_b32_e64 v73, v73, v238, s[0:1]
	v_cmp_eq_u32_e64 s[0:1], 23, v237
	v_cndmask_b32_e64 v74, v74, v238, s[40:41]
	v_cmp_eq_u32_e64 s[40:41], 24, v237
	v_cndmask_b32_e64 v75, v75, v238, vcc
	v_cmp_eq_u32_e64 vcc, 25, v237
	v_cndmask_b32_e64 v76, v76, v238, s[0:1]
	v_cmp_eq_u32_e64 s[0:1], 26, v237
	v_cndmask_b32_e64 v77, v77, v238, s[40:41]
	v_cmp_eq_u32_e64 s[40:41], 27, v237
	v_cndmask_b32_e64 v78, v78, v238, vcc
	v_cmp_eq_u32_e64 vcc, 28, v237
	v_cndmask_b32_e64 v79, v79, v238, s[0:1]
	v_cmp_eq_u32_e64 s[0:1], 29, v237
	v_cndmask_b32_e64 v80, v80, v238, s[40:41]
	s_nop 0
	v_cndmask_b32_e64 v81, v81, v238, vcc
	s_nop 0
	v_cndmask_b32_e64 v234, v234, v238, s[0:1]
	v_mov_b32_e32 v236, -1.0
	v_mov_b32_e32 v237, -1
	v_cmp_gt_f32_e32 vcc, v54, v236
	s_nop 1
	v_cndmask_b32_e32 v236, v236, v54, vcc
	v_cndmask_b32_e64 v237, v237, 1, vcc
	v_cmp_gt_f32_e32 vcc, v55, v236
	s_nop 1
	v_cndmask_b32_e32 v236, v236, v55, vcc
	v_cndmask_b32_e64 v237, v237, 2, vcc
	v_cmp_gt_f32_e32 vcc, v56, v236
	s_nop 1
; DEVI void nsa_item(const Params& p, int l, int item, char* lds_raw, volatile int* nsa_cnt) {
;     ...
;       if (best < 0) break;
;       sel |= 1u << best;
;       ++cnt;
;     }
;     selm[tid] = sel;
;     unsigned om = sel;
; #pragma unroll
;     for (int o = 32; o >= 1; o >>= 1) om |= (unsigned)__shfl_xor((int)om, o);
;     if (tid == 0) selm[64] = om;
;   }
	v_cndmask_b32_e32 v236, v236, v56, vcc
	v_cndmask_b32_e64 v237, v237, 3, vcc
	v_cmp_gt_f32_e32 vcc, v57, v236
	s_nop 1
	v_cndmask_b32_e32 v236, v236, v57, vcc
	v_cndmask_b32_e64 v237, v237, 4, vcc
	v_cmp_gt_f32_e32 vcc, v58, v236
	s_nop 1
	v_cndmask_b32_e32 v236, v236, v58, vcc
	v_cndmask_b32_e64 v237, v237, 5, vcc
	v_cmp_gt_f32_e32 vcc, v59, v236
	s_nop 1
	v_cndmask_b32_e32 v236, v236, v59, vcc
	v_cndmask_b32_e64 v237, v237, 6, vcc
	v_cmp_gt_f32_e32 vcc, v60, v236
	s_nop 1
	v_cndmask_b32_e32 v236, v236, v60, vcc
	v_cndmask_b32_e64 v237, v237, 7, vcc
	v_cmp_gt_f32_e32 vcc, v61, v236
	s_nop 1
	v_cndmask_b32_e32 v236, v236, v61, vcc
	v_cndmask_b32_e64 v237, v237, 8, vcc
	v_cmp_gt_f32_e32 vcc, v62, v236
	s_nop 1
	v_cndmask_b32_e32 v236, v236, v62, vcc
	v_cndmask_b32_e64 v237, v237, 9, vcc
	v_cmp_gt_f32_e32 vcc, v63, v236
	s_nop 1
	v_cndmask_b32_e32 v236, v236, v63, vcc
	v_cndmask_b32_e64 v237, v237, 10, vcc
	v_cmp_gt_f32_e32 vcc, v64, v236
	s_nop 1
	v_cndmask_b32_e32 v236, v236, v64, vcc
	v_cndmask_b32_e64 v237, v237, 11, vcc
	v_cmp_gt_f32_e32 vcc, v65, v236
	s_nop 1
	v_cndmask_b32_e32 v236, v236, v65, vcc
	v_cndmask_b32_e64 v237, v237, 12, vcc
	v_cmp_gt_f32_e32 vcc, v66, v236
	s_nop 1
	v_cndmask_b32_e32 v236, v236, v66, vcc
	v_cndmask_b32_e64 v237, v237, 13, vcc
	v_cmp_gt_f32_e32 vcc, v67, v236
	s_nop 1
	v_cndmask_b32_e32 v236, v236, v67, vcc
	v_cndmask_b32_e64 v237, v237, 14, vcc
	v_cmp_gt_f32_e32 vcc, v68, v236
	s_nop 1
	v_cndmask_b32_e32 v236, v236, v68, vcc
	v_cndmask_b32_e64 v237, v237, 15, vcc
	v_cmp_gt_f32_e32 vcc, v69, v236
	s_nop 1
	v_cndmask_b32_e32 v236, v236, v69, vcc
	v_cndmask_b32_e64 v237, v237, 16, vcc
	v_cmp_gt_f32_e32 vcc, v70, v236
	s_nop 1
	v_cndmask_b32_e32 v236, v236, v70, vcc
	v_cndmask_b32_e64 v237, v237, 17, vcc
	v_cmp_gt_f32_e32 vcc, v71, v236
	s_nop 1
	v_cndmask_b32_e32 v236, v236, v71, vcc
	v_cndmask_b32_e64 v237, v237, 18, vcc
	v_cmp_gt_f32_e32 vcc, v72, v236
	s_nop 1
	v_cndmask_b32_e32 v236, v236, v72, vcc
	v_cndmask_b32_e64 v237, v237, 19, vcc
	v_cmp_gt_f32_e32 vcc, v73, v236
	s_nop 1
	v_cndmask_b32_e32 v236, v236, v73, vcc
	v_cndmask_b32_e64 v237, v237, 20, vcc
	v_cmp_gt_f32_e32 vcc, v74, v236
	s_nop 1
	v_cndmask_b32_e32 v236, v236, v74, vcc
	v_cndmask_b32_e64 v237, v237, 21, vcc
	v_cmp_gt_f32_e32 vcc, v75, v236
	s_nop 1
	v_cndmask_b32_e32 v236, v236, v75, vcc
	v_cndmask_b32_e64 v237, v237, 22, vcc
	v_cmp_gt_f32_e32 vcc, v76, v236
	s_nop 1
	v_cndmask_b32_e32 v236, v236, v76, vcc
	v_cndmask_b32_e64 v237, v237, 23, vcc
	v_cmp_gt_f32_e32 vcc, v77, v236
	s_nop 1
	v_cndmask_b32_e32 v236, v236, v77, vcc
	v_cndmask_b32_e64 v237, v237, 24, vcc
	v_cmp_gt_f32_e32 vcc, v78, v236
	s_nop 1
	v_cndmask_b32_e32 v236, v236, v78, vcc
	v_cndmask_b32_e64 v237, v237, 25, vcc
	v_cmp_gt_f32_e32 vcc, v79, v236
	s_nop 1
	v_cndmask_b32_e32 v236, v236, v79, vcc
	v_cndmask_b32_e64 v237, v237, 26, vcc
	v_cmp_gt_f32_e32 vcc, v80, v236
	s_nop 1
	v_cndmask_b32_e32 v236, v236, v80, vcc
	v_cndmask_b32_e64 v237, v237, 27, vcc
	v_cmp_gt_f32_e32 vcc, v81, v236
	s_nop 1
	v_cndmask_b32_e32 v236, v236, v81, vcc
	v_cndmask_b32_e64 v237, v237, 28, vcc
	v_cmp_gt_f32_e32 vcc, v234, v236
	s_nop 1
	v_cndmask_b32_e32 v236, v236, v234, vcc
	v_cndmask_b32_e64 v237, v237, 29, vcc
	v_cmp_le_i32_e32 vcc, 0, v237
	v_lshlrev_b32_e32 v239, v237, v224
	s_nop 0
	v_cndmask_b32_e32 v239, 0, v239, vcc
	v_or_b32_e32 v51, v51, v239
	v_mov_b32_e32 v53, v51
	v_lshlrev_b32_e32 v50, 7, v247
	v_sub_u32_e32 v50, v52, v50
	ds_write_b32 v50, v53 offset:62208
	ds_bpermute_b32 v50, v202, v53
	s_waitcnt lgkmcnt(0)
	v_or_b32_e32 v50, v50, v53
	ds_bpermute_b32 v51, v201, v50
	s_waitcnt lgkmcnt(0)
	v_or_b32_e32 v50, v51, v50
	v_xor_b32_e32 v51, 8, v225
	v_cmp_lt_i32_e32 vcc, v51, v92
	s_nop 1
	v_cndmask_b32_e32 v51, v225, v51, vcc
	v_lshlrev_b32_e32 v51, 2, v51
	ds_bpermute_b32 v51, v51, v50
	s_waitcnt lgkmcnt(0)
	v_or_b32_e32 v50, v51, v50
	v_xor_b32_e32 v51, 4, v225
	v_cmp_lt_i32_e32 vcc, v51, v92
	s_nop 1
	v_cndmask_b32_e32 v51, v225, v51, vcc
	v_lshlrev_b32_e32 v51, 2, v51
	ds_bpermute_b32 v51, v51, v50
	s_waitcnt lgkmcnt(0)
	v_or_b32_e32 v50, v51, v50
	v_xor_b32_e32 v51, 2, v225
	v_cmp_lt_i32_e32 vcc, v51, v92
	s_nop 1
	v_cndmask_b32_e32 v51, v225, v51, vcc
	v_lshlrev_b32_e32 v51, 2, v51
	ds_bpermute_b32 v51, v51, v50
	s_waitcnt lgkmcnt(0)
	v_or_b32_e32 v50, v51, v50
	v_xor_b32_e32 v51, 1, v225
	v_cmp_lt_i32_e32 vcc, v51, v92
	s_nop 1
	v_cndmask_b32_e32 v51, v225, v51, vcc
	v_lshlrev_b32_e32 v51, 2, v51
	ds_bpermute_b32 v51, v51, v50
	v_cmp_eq_u32_e32 vcc, 0, v247
	s_and_b64 exec, exec, vcc
	s_cbranch_execz .LBB0_498
	s_waitcnt lgkmcnt(0)
	v_or_b32_e32 v50, v51, v50
	v_mov_b32_e32 v51, s26
	ds_write_b32 v51, v50 offset:62464

; DEVI int get_tid() { int t = threadIdx.x & 255; asm volatile("" : "+v"(t)); return t; }
; DEVI void cvt_tile(const float* __restrict__ src, int ld_src, int col0, int valid, bfu* __restrict__ dst, int ld_dst,
;                    char* lds_raw, const float* __restrict__ gain = nullptr) {
;   float* tile = (float*)lds_raw;
;   const int tid = get_tid();
;   __syncthreads();
; #pragma unroll
;   for (int i = 0; i < 4; ++i) {
;     int id = tid + 256 * i;
;     int row = id >> 4, c4 = id & 15;
;     float4 v = make_float4(0.f, 0.f, 0.f, 0.f);
;     if (c4 * 4 < valid) {
;       const f32x4 w = __builtin_nontemporal_load((const f32x4*)(src + (long)row * ld_src + col0 + c4 * 4));
;       v = make_float4(w[0], w[1], w[2], w[3]);
;     }
;     if (gain) { const float gk = gain[row]; v.x *= gk; v.y *= gk; v.z *= gk; v.w *= gk; }
;     float* t = tile + row * 65 + c4 * 4;
;     t[0] = v.x; t[1] = v.y; t[2] = v.z; t[3] = v.w;
;   }
;   __syncthreads();
; DEVI void phase1(const Params& p, int l, char* lds) {
;     ...
;       if (i < 1024) {
;         int kt = i / 64, nt = i % 64;
;         cvt_tile(p.in[22] + (long)l * 1024 * 4096 + (long)kt * 64 * 4096, 4096, nt * 64, 64,
;                  (bfu*)(ws + OFF_WM1) + (long)nt * 64 * LDX + kt * 64, LDX, lds, p.in[21] + l * 1024 + kt * 64);
;         continue;
.LBB0_818:
	s_andn2_b64 vcc, exec, s[0:1]
	s_cbranch_vccnz .LBB0_828
	s_and_b32 s0, s23, 0xfc0
	s_add_i32 s30, s0, 0xfffff700
	s_and_b32 s38, s23, 63
	s_lshl_b64 s[0:1], s[30:31], 14
	s_add_u32 s39, s46, s0
	s_addc_u32 s40, s47, s1
	s_lshl_b64 s[0:1], s[30:31], 2
	s_add_u32 s36, s48, s0
	v_mov_b32_e32 v16, v221
	s_addc_u32 s37, s49, s1
	s_lshl_b32 s0, s38, 8
	v_lshlrev_b32_e32 v0, 2, v16
	v_and_b32_e32 v18, 60, v0
	s_add_u32 s0, s39, s0
	v_ashrrev_i32_e32 v12, 4, v16
	s_addc_u32 s1, s40, 0
	v_lshlrev_b32_e32 v0, 2, v18
	v_ashrrev_i32_e32 v13, 31, v12
	v_lshl_add_u64 v[10:11], s[0:1], 0, v[0:1]
	v_lshlrev_b64 v[2:3], 14, v[12:13]
	v_lshl_add_u64 v[2:3], v[10:11], 0, v[2:3]
	s_waitcnt vmcnt(0) lgkmcnt(0)
	s_barrier
	s_mov_b32 s40, 0x40000
	s_mov_b32 s41, 0
	global_load_dwordx4 v[100:103], v[2:3], off nt
	v_lshl_add_u64 v[6:7], v[2:3], 0, s[40:41]
	global_load_dwordx4 v[104:107], v[6:7], off nt
	v_lshl_add_u64 v[6:7], v[6:7], 0, s[40:41]
	global_load_dwordx4 v[108:111], v[6:7], off nt
	v_lshl_add_u64 v[6:7], v[6:7], 0, s[40:41]
	global_load_dwordx4 v[112:115], v[6:7], off nt
	v_readlane_b32 s40, v243, 38
	v_readlane_b32 s41, v243, 39
	s_andn2_b64 vcc, exec, s[40:41]
	v_lshl_add_u32 v0, v18, 2, s26
	s_movk_i32 s21, 0x104
	v_mad_u32_u24 v12, v12, s21, v0
	v_add_u32_e32 v13, 0x1040, v12
	v_add_u32_e32 v14, 0x2080, v12
	v_add_u32_e32 v15, 0x30c0, v12
	v_add_u32_e32 v17, 0x100, v16
	s_cbranch_vccnz .Lwm1_nogain
	v_mov_b32_e32 v7, 0
	v_ashrrev_i32_e32 v6, 4, v16
	v_lshl_add_u64 v[6:7], v[6:7], 2, s[36:37]
	global_load_dword v116, v[6:7], off
	global_load_dword v118, v[6:7], off offset:64
	global_load_dword v120, v[6:7], off offset:128
	global_load_dword v122, v[6:7], off offset:192
	s_waitcnt vmcnt(0)
	v_pk_mul_f32 v[100:101], v[100:101], v[116:117] op_sel_hi:[1,0]
	v_pk_mul_f32 v[102:103], v[102:103], v[116:117] op_sel_hi:[1,0]
	v_pk_mul_f32 v[104:105], v[104:105], v[118:119] op_sel_hi:[1,0]
	v_pk_mul_f32 v[106:107], v[106:107], v[118:119] op_sel_hi:[1,0]
	v_pk_mul_f32 v[108:109], v[108:109], v[120:121] op_sel_hi:[1,0]
	v_pk_mul_f32 v[110:111], v[110:111], v[120:121] op_sel_hi:[1,0]
	v_pk_mul_f32 v[112:113], v[112:113], v[122:123] op_sel_hi:[1,0]
	v_pk_mul_f32 v[114:115], v[114:115], v[122:123] op_sel_hi:[1,0]
.Lwm1_nogain:
	s_waitcnt vmcnt(0)
	ds_write2_b32 v12, v100, v101 offset1:1
	ds_write2_b32 v12, v102, v103 offset0:2 offset1:3
	ds_write2_b32 v13, v104, v105 offset1:1
	ds_write2_b32 v13, v106, v107 offset0:2 offset1:3
	ds_write2_b32 v14, v108, v109 offset1:1
	ds_write2_b32 v14, v110, v111 offset0:2 offset1:3
	ds_write2_b32 v15, v112, v113 offset1:1
	ds_write2_b32 v15, v114, v115 offset0:2 offset1:3
.LBB0_827:
	s_mul_i32 s38, s38, 0x22000
	v_readlane_b32 s0, v244, 63
	s_add_u32 s36, s0, s38
	v_readlane_b32 s0, v243, 0
	s_addc_u32 s37, s0, 0
	s_lshl_b64 s[0:1], s[30:31], 1
	s_add_u32 s0, s36, s0
	s_addc_u32 s1, s37, s1
	v_lshlrev_b32_e32 v0, 3, v16
	s_waitcnt vmcnt(0)
	v_and_b32_e32 v2, 56, v0
	v_mov_b32_e32 v3, s26
	v_ashrrev_i32_e32 v12, 3, v16
	v_mad_u32_u24 v13, v2, s21, v3
	v_lshl_add_u32 v6, v12, 2, v13
	v_add_u32_e32 v8, 0x400, v6
	s_waitcnt lgkmcnt(0)
	s_barrier
	v_lshlrev_b32_e32 v0, 1, v2
	ds_read2_b32 v[2:3], v6 offset1:65
	ds_read2_b32 v[4:5], v6 offset0:130 offset1:195
	ds_read2_b32 v[6:7], v8 offset0:4 offset1:69
	ds_read2_b32 v[8:9], v8 offset0:134 offset1:199
	v_lshl_add_u64 v[10:11], s[0:1], 0, v[0:1]
	v_ashrrev_i32_e32 v0, 3, v17
	v_lshl_add_u32 v14, v0, 2, v13
	v_add_u32_e32 v16, 0x400, v14
	s_waitcnt lgkmcnt(3)
	v_cvt_pk_bf16_f32 v2, v2, v3
	s_waitcnt lgkmcnt(2)
	v_cvt_pk_bf16_f32 v3, v4, v5
	s_waitcnt lgkmcnt(1)
	v_cvt_pk_bf16_f32 v4, v6, v7
	s_waitcnt lgkmcnt(0)
	v_cvt_pk_bf16_f32 v5, v8, v9
	v_mad_i64_i32 v[6:7], s[0:1], v12, s95, v[10:11]
	ds_read2_b32 v[8:9], v14 offset1:65
	ds_read2_b32 v[12:13], v14 offset0:130 offset1:195
	ds_read2_b32 v[14:15], v16 offset0:4 offset1:69
	ds_read2_b32 v[16:17], v16 offset0:134 offset1:199
	global_store_dwordx4 v[6:7], v[2:5], off
	v_mad_i64_i32 v[6:7], s[0:1], v0, s95, v[10:11]
	s_waitcnt lgkmcnt(3)
	v_cvt_pk_bf16_f32 v2, v8, v9
	s_waitcnt lgkmcnt(2)
	v_cvt_pk_bf16_f32 v3, v12, v13
	s_waitcnt lgkmcnt(1)
	v_cvt_pk_bf16_f32 v4, v14, v15
	s_waitcnt lgkmcnt(0)
	v_cvt_pk_bf16_f32 v5, v16, v17
	global_store_dwordx4 v[6:7], v[2:5], off
